# attention main loop software-pipelined: QK(t) then PV(t-1) interleaved with exp(t), K/V fragment rings
# speedup vs baseline: 1.0116x; 1.0116x over previous
; #define LAS __attribute__((address_space(3)))
; __device__ __forceinline__ int my_tid() { int t = threadIdx.x; asm volatile("" : "+v"(t)); return t; }
; #define ATT_LOAD(tile) do { _Pragma("unroll") for (int i = 0; i < 2; ++i) { kr[i] = *(const u32x4*)(kg + (size_t)(64 * (tile) + 32 * i) * PP); vr[i] = *(const u32x4*)(vg + (size_t)(64 * (tile) + 32 * i) * PP); } } while (0)
; #define ATT_STORE(buf) do { LAS char* nb_ = lds + (buf) * ABUF; _Pragma("unroll") for (int i = 0; i < 2; ++i) { *(LAS u32x4*)(nb_ + soff + 32 * i * APIT) = kr[i]; *(LAS u32x4*)(nb_ + ATILE + soff + 32 * i * APIT) = vr[i]; } } while (0)
; __device__ __forceinline__ void attn_item(LAS char* lds, bf16_t* proj, int bl, int h, int qb, float lam, float oscale, const float* gdh, float smax) {
;     const int tid = my_tid(), lane = tid & 63, wid = __builtin_amdgcn_readfirstlane(tid >> 6), g = lane >> 4, fr = lane & 15;
;     const size_t rowbase = (size_t)bl * SEQ; const int q0 = qb * 128, qpos = q0 + 16 * wid + fr;
;     bf16_t* qp = proj + SEC(C_AQ) + (rowbase + qpos) * PP + h * 128;
;     bf16x8 qf[2][2];
; #pragma unroll
;     for (int c = 0; c < 2; ++c)
; #pragma unroll
;         for (int ks = 0; ks < 2; ++ks) qf[c][ks] = *(const bf16x8*)(qp + c * 64 + 32 * ks + 8 * g);
;     f32x4 O[2][8], Oe[2];
; #pragma unroll
;     for (int c = 0; c < 2; ++c) { Oe[c] = (f32x4){0.f, 0.f, 0.f, 0.f};
; #pragma unroll
;         for (int nb = 0; nb < 8; ++nb) O[c][nb] = (f32x4){0.f, 0.f, 0.f, 0.f}; }
;     const f32x4 negM = (f32x4){-smax, -smax, -smax, -smax};
;     const short one16 = (fr == 0) ? (short)0x3F80 : (short)0;
;     const bf16x8 onesf = (bf16x8){one16, one16, one16, one16, one16, one16, one16, one16};
;     const int NT = 2 * (qb + 1);
;     const int sr0 = tid >> 4, sc = tid & 15;
;     const bf16_t* kg = proj + SEC(C_AK) + (rowbase + sr0) * PP + h * 128 + sc * 8;
;     const bf16_t* vg = proj + SEC(C_AV) + (rowbase + sr0) * PP + h * 128 + sc * 8;
;     const int soff = sr0 * APIT + sc * 16;
;     u32x4 kr[2], vr[2];
;     ...
;     ATT_LOAD(0); ATT_STORE(0);
;     __syncthreads();
;     const int qmaxw = q0 + 16 * wid + 15;
;     int t = 0;
;     for (; t < NT - 2; ++t) {
;         ATT_LOAD(t + 1);
;         const LAS char* Kb = lds + (t & 1) * ABUF;
.LBB0_241:
	s_and_b32 s0, s40, 7
	s_lshl_b32 s44, s0, 8
	s_bfe_u32 s0, s41, 0x50003
	s_and_b32 s42, s41, 7
	s_and_b32 s1, s41, 0x100
	s_xor_b32 s4, s0, 31
	s_cmp_eq_u32 s1, 0
	v_mov_b32_e32 v14, v194
	s_cselect_b32 s45, s0, s4
	s_lshl_b32 s46, s45, 7
	v_readfirstlane_b32 s4, v14
	s_ashr_i32 s4, s4, 2
	s_and_b32 s43, s4, -16
	s_ashr_i32 s36, s41, 8
	v_and_b32_e32 v176, 15, v14
	s_add_i32 s43, s43, s46
	s_ashr_i32 s37, s36, 31
	v_or_b32_e32 v164, s43, v176
	s_lshl_b64 s[0:1], s[36:37], 12
	v_ashrrev_i32_e32 v165, 31, v164
	v_lshl_add_u64 v[162:163], s[0:1], 0, v[164:165]
	v_readlane_b32 s4, v252, 28
	v_lshlrev_b64 v[6:7], 11, v[162:163]
	v_readlane_b32 s5, v252, 29
	s_lshl_b32 s84, s42, 8
	v_lshlrev_b32_e32 v0, 4, v176
	v_lshl_add_u64 v[6:7], s[4:5], 0, v[6:7]
	v_lshl_add_u64 v[8:9], v[6:7], 0, s[84:85]
	v_ashrrev_i32_e32 v6, 4, v14
	v_ashrrev_i32_e32 v7, 31, v6
	v_lshl_add_u64 v[10:11], s[0:1], 0, v[6:7]
	v_readlane_b32 s0, v252, 30
	v_lshlrev_b64 v[10:11], 11, v[10:11]
	v_readlane_b32 s1, v252, 31
	v_and_b32_e32 v166, 48, v14
	v_mov_b32_e32 v167, v1
	v_lshl_add_u64 v[12:13], s[0:1], 0, v[10:11]
	v_readlane_b32 s0, v252, 32
	v_readlane_b32 s1, v252, 33
	v_lshl_add_u64 v[12:13], v[12:13], 0, s[84:85]
	v_lshl_add_u64 v[12:13], v[12:13], 0, v[0:1]
	v_lshl_add_u64 v[10:11], s[0:1], 0, v[10:11]
	v_lshl_add_u64 v[10:11], v[10:11], 0, s[84:85]
	s_mov_b32 s0, 0x10000
	v_lshl_add_u64 v[10:11], v[10:11], 0, v[0:1]
	global_load_dwordx4 v[118:121], v[12:13], off
	global_load_dwordx4 v[114:117], v[10:11], off
	v_add_co_u32_e32 v12, vcc, s0, v12
	v_lshl_add_u64 v[8:9], v[8:9], 0, v[166:167]
	s_nop 0
	v_addc_co_u32_e32 v13, vcc, 0, v13, vcc
	v_add_co_u32_e32 v10, vcc, s0, v10
	s_movk_i32 s0, 0x120
	s_nop 0
	v_addc_co_u32_e32 v11, vcc, 0, v11, vcc
	global_load_dwordx4 v[122:125], v[12:13], off
	global_load_dwordx4 v[126:129], v[10:11], off
	global_load_dwordx4 v[34:37], v[8:9], off
	global_load_dwordx4 v[38:41], v[8:9], off offset:64
	global_load_dwordx4 v[42:45], v[8:9], off offset:128
	global_load_dwordx4 v[50:53], v[8:9], off offset:192
	v_cmp_eq_u32_e32 vcc, 0, v176
	v_mov_b32_e32 v11, 0x3f80
	v_and_b32_e32 v8, 63, v14
	v_cndmask_b32_e32 v11, 0, v11, vcc
	v_mul_lo_u32 v12, v6, s0
	s_mov_b32 s0, 0x5040100
	v_bfe_u32 v9, v14, 2, 4
	v_lshlrev_b32_e32 v10, 3, v14
	v_or_b32_e32 v8, 48, v8
	v_perm_b32 v74, v11, v11, s0
	v_mul_u32_u24_e32 v167, 0x120, v176
	v_and_b32_e32 v165, 12, v9
	v_mul_u32_u24_e32 v177, 0x120, v9
	v_and_b32_e32 v178, 24, v10
	v_add3_u32 v179, v12, v0, 0
	v_mul_u32_u24_e32 v180, 0x120, v8
	v_mov_b32_e32 v75, v74
	v_mov_b32_e32 v76, v74
	v_mov_b32_e32 v77, v74
	s_cmp_lg_u32 s45, 0
	v_lshlrev_b64 v[170:171], 11, v[6:7]
	s_waitcnt vmcnt(7)
	ds_write_b128 v179, v[118:121]
	s_waitcnt vmcnt(6)
	ds_write_b128 v179, v[114:117] offset:18432
	s_waitcnt vmcnt(5)
	ds_write_b128 v179, v[122:125] offset:9216
	s_waitcnt vmcnt(4)
	ds_write_b128 v179, v[126:129] offset:27648
	s_waitcnt lgkmcnt(0)
	s_barrier
	s_cbranch_scc0 .LBB0_259
	s_lshl_b64 s[38:39], s[36:37], 23
	v_lshlrev_b64 v[168:169], 11, v[6:7]
	v_lshl_add_u64 v[6:7], s[38:39], 0, v[168:169]
	v_or_b32_e32 v6, s44, v6
	v_readlane_b32 s0, v254, 29
	v_lshl_add_u64 v[6:7], v[6:7], 0, v[0:1]
	v_readlane_b32 s1, v254, 30
	v_mov_b32_e32 v86, 0
	s_mov_b32 s47, 0
	v_lshl_add_u64 v[172:173], s[0:1], 0, v[6:7]
	s_mov_b32 s48, 1
	v_mov_b32_e32 v87, v86
	v_mov_b32_e32 v88, v86
	v_mov_b32_e32 v89, v86
	v_mov_b32_e32 v66, v86
	v_mov_b32_e32 v67, v86
	v_mov_b32_e32 v68, v86
	v_mov_b32_e32 v69, v86
	v_mov_b32_e32 v10, v86
	v_mov_b32_e32 v11, v86
	v_mov_b32_e32 v12, v86
	v_mov_b32_e32 v13, v86
	v_mov_b32_e32 v6, v86
	v_mov_b32_e32 v7, v86
	v_mov_b32_e32 v8, v86
	v_mov_b32_e32 v9, v86
	v_mov_b32_e32 v14, v86
	v_mov_b32_e32 v15, v86
	v_mov_b32_e32 v16, v86
	v_mov_b32_e32 v17, v86
	v_mov_b32_e32 v18, v86
	v_mov_b32_e32 v19, v86
	v_mov_b32_e32 v20, v86
	v_mov_b32_e32 v21, v86
	v_mov_b32_e32 v22, v86
	v_mov_b32_e32 v23, v86
	v_mov_b32_e32 v24, v86
	v_mov_b32_e32 v25, v86
	v_mov_b32_e32 v26, v86
	v_mov_b32_e32 v27, v86
	v_mov_b32_e32 v28, v86
	v_mov_b32_e32 v29, v86
	v_mov_b32_e32 v30, v86
	v_mov_b32_e32 v31, v86
	v_mov_b32_e32 v32, v86
	v_mov_b32_e32 v33, v86
	v_mov_b32_e32 v46, v86
	v_mov_b32_e32 v47, v86
	v_mov_b32_e32 v48, v86
	v_mov_b32_e32 v49, v86
	v_mov_b32_e32 v54, v86
	v_mov_b32_e32 v55, v86
	v_mov_b32_e32 v56, v86
	v_mov_b32_e32 v57, v86
	v_mov_b32_e32 v58, v86
	v_mov_b32_e32 v59, v86
	v_mov_b32_e32 v60, v86
	v_mov_b32_e32 v61, v86
	v_mov_b32_e32 v62, v86
	v_mov_b32_e32 v63, v86
	v_mov_b32_e32 v64, v86
	v_mov_b32_e32 v65, v86
	v_mov_b32_e32 v70, v86
	v_mov_b32_e32 v71, v86
	v_mov_b32_e32 v72, v86
	v_mov_b32_e32 v73, v86
	v_mov_b32_e32 v78, v86
	v_mov_b32_e32 v79, v86
	v_mov_b32_e32 v80, v86
	v_mov_b32_e32 v81, v86
	v_mov_b32_e32 v90, v86
	v_mov_b32_e32 v91, v86
	v_mov_b32_e32 v92, v86
	v_mov_b32_e32 v93, v86
	v_mov_b32_e32 v94, v86
	v_mov_b32_e32 v95, v86
	v_mov_b32_e32 v96, v86
	v_mov_b32_e32 v97, v86
	v_mov_b32_e32 v82, v86
	v_mov_b32_e32 v83, v86
	v_mov_b32_e32 v84, v86
	v_mov_b32_e32 v85, v86
	v_add_u32_e32 v230, v166, v167
	v_add_u32_e32 v231, v177, v178
	s_mov_b32 s4, 0xfdff0000
	s_mov_b32 s5, -1
	s_mov_b32 s6, 0xfe000000
	s_mov_b32 s7, -1
	s_mov_b32 s8, 0xfffd0000
	s_mov_b32 s9, -1
	s_mov_b32 s10, 0xfffe0000
	s_mov_b32 s11, -1
	s_mov_b32 s49, 0
	s_mov_b32 s50, 0x9000
	v_add_u32_e32 v181, s49, v230
	ds_read_b128 v[206:209], v181
	ds_read_b128 v[210:213], v181 offset:64
	ds_read_b128 v[214:217], v181 offset:4608
	ds_read_b128 v[218:221], v181 offset:4672
	ds_read_b128 v[222:225], v181 offset:9216
	v_lshl_add_u64 v[240:241], v[172:173], 0, s[4:5]
	global_load_dwordx4 v[146:149], v[240:241], off
	v_lshl_add_u64 v[240:241], v[172:173], 0, s[6:7]
	global_load_dwordx4 v[150:153], v[240:241], off
	v_lshl_add_u64 v[172:173], v[172:173], 0, s[76:77]
	s_waitcnt vmcnt(2)
; #define LAS __attribute__((address_space(3)))
; __device__ __forceinline__ f32x4 mfma16(bf16x8 a, bf16x8 b, f32x4 c) { return __builtin_amdgcn_mfma_f32_16x16x32_bf16(a, b, c, 0, 0, 0); }
; #define BAR_LDS() do { asm volatile("s_waitcnt lgkmcnt(0)" ::: "memory"); __builtin_amdgcn_s_barrier(); asm volatile("" ::: "memory"); } while (0)
; #define ATT_LOAD(tile) do { _Pragma("unroll") for (int i = 0; i < 2; ++i) { kr[i] = *(const u32x4*)(kg + (size_t)(64 * (tile) + 32 * i) * PP); vr[i] = *(const u32x4*)(vg + (size_t)(64 * (tile) + 32 * i) * PP); } } while (0)
; __device__ __forceinline__ void attn_step_fast(const LAS char* Kb, const LAS char* Vb, int lane, const bf16x8 (&qf)[2][2], const f32x4 negM, const bf16x8 onesf, f32x4 (&O)[2][8], f32x4 (&Oe)[2]) {
;     f32x4 s0[4], s1[4];
;     bf16x8 p0[2], p1[2];
;     {
;         bf16x8 kf[2][4][2];
; #pragma unroll
;         for (int c = 0; c < 2; ++c)
; #pragma unroll
;             for (int kb = 0; kb < 4; ++kb)
; #pragma unroll
;                 for (int ks = 0; ks < 2; ++ks) kf[c][kb][ks] = rowfrag(Kb, APIT, 16 * kb, c * 64 + 32 * ks, lane);
;         __builtin_amdgcn_sched_barrier(0);
; #pragma unroll
;         for (int kb = 0; kb < 4; ++kb) s0[kb] = mfma16(kf[0][kb][0], qf[0][0], negM);
; #pragma unroll
;         for (int kb = 0; kb < 4; ++kb) s0[kb] = mfma16(kf[0][kb][1], qf[0][1], s0[kb]);
;         __builtin_amdgcn_sched_barrier(0);
; #pragma unroll
;         for (int kb = 0; kb < 4; ++kb) s1[kb] = mfma16(kf[1][kb][0], qf[1][0], negM);
; #pragma unroll
;         for (int kb = 0; kb < 4; ++kb) s1[kb] = mfma16(kf[1][kb][1], qf[1][1], s1[kb]);
;     }
;     ...
;     ATT_EXPPACK(s0, p0);
; __device__ __forceinline__ void attn_item(LAS char* lds, bf16_t* proj, int bl, int h, int qb, float lam, float oscale, const float* gdh, float smax) {
;     ...
;     for (; t < NT - 2; ++t) {
;         ATT_LOAD(t + 1);
;         const LAS char* Kb = lds + (t & 1) * ABUF;
;     ...
;         attn_step_fast(Kb, Kb + ATILE, lane, qf, negM, onesf, O, Oe);
;     ...
;         { bf16x8 pq[2][2]; attn_qkexp(Kb, 64 * t, q0, wid, lane, g, qpos, qf, negM, pq); attn_pv(Kb + ATILE, lane, pq, onesf, O, Oe); }
;     ...
;         ATT_STORE((t + 1) & 1);
;         BAR_LDS();
	s_waitcnt lgkmcnt(4)
	v_mfma_f32_16x16x32_bf16 v[98:101], v[206:209], v[34:37], v[2:5]
	ds_read_b128 v[206:209], v181 offset:9280
	s_waitcnt lgkmcnt(4)
	v_mfma_f32_16x16x32_bf16 v[98:101], v[210:213], v[38:41], v[98:101]
	ds_read_b128 v[210:213], v181 offset:13824
	s_waitcnt lgkmcnt(4)
	v_mfma_f32_16x16x32_bf16 v[102:105], v[214:217], v[34:37], v[2:5]
	ds_read_b128 v[214:217], v181 offset:13888
	s_waitcnt lgkmcnt(4)
	v_mfma_f32_16x16x32_bf16 v[102:105], v[218:221], v[38:41], v[102:105]
	ds_read_b128 v[218:221], v181 offset:128
	s_waitcnt lgkmcnt(4)
	v_mfma_f32_16x16x32_bf16 v[106:109], v[222:225], v[34:37], v[2:5]
	ds_read_b128 v[222:225], v181 offset:192
	s_waitcnt lgkmcnt(4)
	v_mfma_f32_16x16x32_bf16 v[106:109], v[206:209], v[38:41], v[106:109]
	ds_read_b128 v[206:209], v181 offset:4736
	s_waitcnt lgkmcnt(4)
	v_mfma_f32_16x16x32_bf16 v[110:113], v[210:213], v[34:37], v[2:5]
	ds_read_b128 v[210:213], v181 offset:4800
	s_waitcnt lgkmcnt(4)
	v_mfma_f32_16x16x32_bf16 v[110:113], v[214:217], v[38:41], v[110:113]
	ds_read_b128 v[214:217], v181 offset:9344
	s_waitcnt lgkmcnt(4)
	v_mfma_f32_16x16x32_bf16 v[114:117], v[218:221], v[42:45], v[2:5]
	ds_read_b128 v[218:221], v181 offset:9408
	s_waitcnt lgkmcnt(4)
	v_mfma_f32_16x16x32_bf16 v[114:117], v[222:225], v[50:53], v[114:117]
	ds_read_b128 v[222:225], v181 offset:13952
	s_waitcnt lgkmcnt(4)
	v_mfma_f32_16x16x32_bf16 v[118:121], v[206:209], v[42:45], v[2:5]
	ds_read_b128 v[206:209], v181 offset:14016
	s_waitcnt lgkmcnt(4)
	v_mfma_f32_16x16x32_bf16 v[118:121], v[210:213], v[50:53], v[118:121]
	s_waitcnt lgkmcnt(3)
	v_mfma_f32_16x16x32_bf16 v[122:125], v[214:217], v[42:45], v[2:5]
	s_waitcnt lgkmcnt(2)
	v_mfma_f32_16x16x32_bf16 v[122:125], v[218:221], v[50:53], v[122:125]
	s_waitcnt lgkmcnt(1)
	v_mfma_f32_16x16x32_bf16 v[126:129], v[222:225], v[42:45], v[2:5]
	s_waitcnt lgkmcnt(0)
	v_mfma_f32_16x16x32_bf16 v[126:129], v[206:209], v[50:53], v[126:129]
	v_add_u32_e32 v238, s50, v179
	s_nop 7
	v_exp_f32_e32 v98, v98
	v_exp_f32_e32 v99, v99
	v_exp_f32_e32 v100, v100
	v_exp_f32_e32 v101, v101
	v_exp_f32_e32 v114, v114
	v_exp_f32_e32 v115, v115
	v_exp_f32_e32 v116, v116
	v_exp_f32_e32 v117, v117
	v_exp_f32_e32 v102, v102
	v_exp_f32_e32 v103, v103
	v_exp_f32_e32 v104, v104
	v_exp_f32_e32 v105, v105
	v_exp_f32_e32 v118, v118
	v_exp_f32_e32 v119, v119
	v_exp_f32_e32 v120, v120
	v_exp_f32_e32 v121, v121
	v_exp_f32_e32 v106, v106
	v_exp_f32_e32 v107, v107
	v_exp_f32_e32 v108, v108
	v_exp_f32_e32 v109, v109
	v_exp_f32_e32 v122, v122
	v_exp_f32_e32 v123, v123
	v_exp_f32_e32 v124, v124
	v_exp_f32_e32 v125, v125
	v_exp_f32_e32 v110, v110
	v_exp_f32_e32 v111, v111
	v_exp_f32_e32 v112, v112
	v_exp_f32_e32 v113, v113
	v_exp_f32_e32 v126, v126
	v_exp_f32_e32 v127, v127
	v_exp_f32_e32 v128, v128
	v_exp_f32_e32 v129, v129
	v_cvt_pk_bf16_f32 v130, v98, v99
	v_cvt_pk_bf16_f32 v131, v100, v101
	v_cvt_pk_bf16_f32 v132, v102, v103
	v_cvt_pk_bf16_f32 v133, v104, v105
	v_cvt_pk_bf16_f32 v138, v114, v115
	v_cvt_pk_bf16_f32 v139, v116, v117
	v_cvt_pk_bf16_f32 v140, v118, v119
	v_cvt_pk_bf16_f32 v141, v120, v121
	s_waitcnt vmcnt(1)
	ds_write_b128 v238, v[146:149]
	s_waitcnt vmcnt(0)
	ds_write_b128 v238, v[150:153] offset:9216
	s_waitcnt lgkmcnt(0)
	s_barrier
	s_lshl_b32 s47, s45, 1
	s_add_i32 s47, s47, -1
	s_mov_b32 s49, 0x9000
	s_mov_b32 s50, 0
.Lmy_attn_loop:
	v_add_u32_e32 v181, s49, v230
	v_add_u32_e32 v205, s50, v231
	ds_read_b128 v[206:209], v181
	ds_read_b128 v[210:213], v181 offset:64
	ds_read_b128 v[214:217], v181 offset:4608
	ds_read_b128 v[218:221], v181 offset:4672
	ds_read_b128 v[222:225], v181 offset:9216
	v_lshl_add_u64 v[240:241], v[172:173], 0, s[4:5]
	global_load_dwordx4 v[146:149], v[240:241], off
	v_lshl_add_u64 v[240:241], v[172:173], 0, s[6:7]
	global_load_dwordx4 v[150:153], v[240:241], off
	v_lshl_add_u64 v[240:241], v[172:173], 0, s[8:9]
	global_load_dwordx4 v[154:157], v[240:241], off
	v_lshl_add_u64 v[240:241], v[172:173], 0, s[10:11]
	global_load_dwordx4 v[158:161], v[240:241], off
	v_lshl_add_u64 v[172:173], v[172:173], 0, s[76:77]
	v_cvt_pk_bf16_f32 v134, v106, v107
	v_cvt_pk_bf16_f32 v135, v108, v109
	v_cvt_pk_bf16_f32 v136, v110, v111
	v_cvt_pk_bf16_f32 v137, v112, v113
	v_cvt_pk_bf16_f32 v142, v122, v123
	v_cvt_pk_bf16_f32 v143, v124, v125
	v_cvt_pk_bf16_f32 v144, v126, v127
	v_cvt_pk_bf16_f32 v145, v128, v129
	s_waitcnt lgkmcnt(4)
	v_mfma_f32_16x16x32_bf16 v[98:101], v[206:209], v[34:37], v[2:5]
	ds_read_b128 v[206:209], v181 offset:9280
	s_waitcnt lgkmcnt(4)
	v_mfma_f32_16x16x32_bf16 v[98:101], v[210:213], v[38:41], v[98:101]
	ds_read_b128 v[210:213], v181 offset:13824
	s_waitcnt lgkmcnt(4)
	v_mfma_f32_16x16x32_bf16 v[102:105], v[214:217], v[34:37], v[2:5]
	ds_read_b128 v[214:217], v181 offset:13888
	s_waitcnt lgkmcnt(4)
	v_mfma_f32_16x16x32_bf16 v[102:105], v[218:221], v[38:41], v[102:105]
	ds_read_b128 v[218:221], v181 offset:128
	s_waitcnt lgkmcnt(4)
	v_mfma_f32_16x16x32_bf16 v[106:109], v[222:225], v[34:37], v[2:5]
	ds_read_b128 v[222:225], v181 offset:192
	s_waitcnt lgkmcnt(4)
	v_mfma_f32_16x16x32_bf16 v[106:109], v[206:209], v[38:41], v[106:109]
	ds_read_b128 v[206:209], v181 offset:4736
	s_waitcnt lgkmcnt(4)
	v_mfma_f32_16x16x32_bf16 v[110:113], v[210:213], v[34:37], v[2:5]
	ds_read_b128 v[210:213], v181 offset:4800
	s_waitcnt lgkmcnt(4)
	v_mfma_f32_16x16x32_bf16 v[110:113], v[214:217], v[38:41], v[110:113]
	ds_read_b128 v[214:217], v181 offset:9344
	s_waitcnt lgkmcnt(4)
	v_mfma_f32_16x16x32_bf16 v[114:117], v[218:221], v[42:45], v[2:5]
	ds_read_b128 v[218:221], v181 offset:9408
	s_waitcnt lgkmcnt(4)
	v_mfma_f32_16x16x32_bf16 v[114:117], v[222:225], v[50:53], v[114:117]
	ds_read_b128 v[222:225], v181 offset:13952
	s_waitcnt lgkmcnt(4)
; __device__ __forceinline__ f32x4 mfma16(bf16x8 a, bf16x8 b, f32x4 c) { return __builtin_amdgcn_mfma_f32_16x16x32_bf16(a, b, c, 0, 0, 0); }
; __device__ __forceinline__ void attn_step_fast(const LAS char* Kb, const LAS char* Vb, int lane, const bf16x8 (&qf)[2][2], const f32x4 negM, const bf16x8 onesf, f32x4 (&O)[2][8], f32x4 (&Oe)[2]) {
;     ...
;     ATT_EXPPACK(s0, p0);
; #pragma unroll
;     for (int i = 0; i < 8; ++i) { __builtin_amdgcn_sched_group_barrier(0x008, 1, 0); __builtin_amdgcn_sched_group_barrier(0x002, 3, 0); }
;     __builtin_amdgcn_sched_barrier(0);
;     bf16x8 va[8], vb[8];
; #pragma unroll
;     for (int nb = 0; nb < 8; ++nb) va[nb] = trfrag(Vb, APIT, 0, 16 * nb, lane);
; #pragma unroll
;     for (int nb = 0; nb < 8; ++nb) vb[nb] = trfrag(Vb, APIT, 32, 16 * nb, lane);
;     __builtin_amdgcn_sched_barrier(0);
;     Oe[0] = mfma16(onesf, p0[0], Oe[0]);
; #pragma unroll
;     for (int nb = 0; nb < 8; ++nb) O[0][nb] = mfma16(va[nb], p0[0], O[0][nb]);
;     Oe[0] = mfma16(onesf, p0[1], Oe[0]);
; #pragma unroll
;     for (int nb = 0; nb < 8; ++nb) O[0][nb] = mfma16(vb[nb], p0[1], O[0][nb]);
;     ATT_EXPPACK(s1, p1);
; #pragma unroll
;     for (int i = 0; i < 18; ++i) { __builtin_amdgcn_sched_group_barrier(0x008, 1, 0); __builtin_amdgcn_sched_group_barrier(0x002, 2, 0); }
;     __builtin_amdgcn_sched_barrier(0);
;     Oe[1] = mfma16(onesf, p1[0], Oe[1]);
; #pragma unroll
;     for (int nb = 0; nb < 8; ++nb) O[1][nb] = mfma16(va[nb], p1[0], O[1][nb]);
;     Oe[1] = mfma16(onesf, p1[1], Oe[1]);
; #pragma unroll
;     for (int nb = 0; nb < 8; ++nb) O[1][nb] = mfma16(vb[nb], p1[1], O[1][nb]);
	v_mfma_f32_16x16x32_bf16 v[118:121], v[206:209], v[42:45], v[2:5]
	ds_read_b128 v[206:209], v181 offset:14016
	ds_read_b64_tr_b16 v[182:183], v205 offset:18432
	ds_read_b64_tr_b16 v[184:185], v205 offset:23040
	s_waitcnt lgkmcnt(6)
	v_mfma_f32_16x16x32_bf16 v[118:121], v[210:213], v[50:53], v[118:121]
	ds_read_b64_tr_b16 v[186:187], v205 offset:18464
	ds_read_b64_tr_b16 v[188:189], v205 offset:23072
	s_waitcnt lgkmcnt(7)
	v_mfma_f32_16x16x32_bf16 v[122:125], v[214:217], v[42:45], v[2:5]
	ds_read_b64_tr_b16 v[190:191], v205 offset:18496
	ds_read_b64_tr_b16 v[192:193], v205 offset:23104
	s_waitcnt lgkmcnt(8)
	v_mfma_f32_16x16x32_bf16 v[122:125], v[218:221], v[50:53], v[122:125]
	ds_read_b64_tr_b16 v[226:227], v205 offset:18528
	ds_read_b64_tr_b16 v[228:229], v205 offset:23136
	s_waitcnt lgkmcnt(9)
	v_mfma_f32_16x16x32_bf16 v[126:129], v[222:225], v[42:45], v[2:5]
	ds_read_b64_tr_b16 v[244:245], v205 offset:18560
	ds_read_b64_tr_b16 v[246:247], v205 offset:23168
	s_waitcnt lgkmcnt(10)
	v_mfma_f32_16x16x32_bf16 v[126:129], v[206:209], v[50:53], v[126:129]
	ds_read_b64_tr_b16 v[248:249], v205 offset:18592
	ds_read_b64_tr_b16 v[250:251], v205 offset:23200
	v_add_u32_e32 v238, s50, v179
	v_add_u32_e32 v239, s49, v179
	v_mfma_f32_16x16x32_bf16 v[94:97], v[74:77], v[130:133], v[94:97]
	v_exp_f32_e32 v98, v98
	v_mfma_f32_16x16x32_bf16 v[90:93], v[74:77], v[138:141], v[90:93]
	v_exp_f32_e32 v99, v99
	s_waitcnt lgkmcnt(10)
	v_mfma_f32_16x16x32_bf16 v[82:85], v[182:185], v[130:133], v[82:85]
	v_exp_f32_e32 v100, v100
	v_mfma_f32_16x16x32_bf16 v[78:81], v[182:185], v[138:141], v[78:81]
	ds_read_b64_tr_b16 v[182:183], v205 offset:18624
	ds_read_b64_tr_b16 v[184:185], v205 offset:23232
	v_exp_f32_e32 v101, v101
	s_waitcnt lgkmcnt(10)
	v_mfma_f32_16x16x32_bf16 v[70:73], v[186:189], v[130:133], v[70:73]
	v_exp_f32_e32 v114, v114
	v_mfma_f32_16x16x32_bf16 v[62:65], v[186:189], v[138:141], v[62:65]
	ds_read_b64_tr_b16 v[186:187], v205 offset:18656
	ds_read_b64_tr_b16 v[188:189], v205 offset:23264
	v_exp_f32_e32 v115, v115
	s_waitcnt lgkmcnt(10)
	v_mfma_f32_16x16x32_bf16 v[58:61], v[190:193], v[130:133], v[58:61]
	v_exp_f32_e32 v116, v116
	v_mfma_f32_16x16x32_bf16 v[54:57], v[190:193], v[138:141], v[54:57]
	ds_read_b64_tr_b16 v[190:191], v205 offset:27648
	ds_read_b64_tr_b16 v[192:193], v205 offset:32256
	v_exp_f32_e32 v117, v117
	s_waitcnt lgkmcnt(10)
	v_mfma_f32_16x16x32_bf16 v[46:49], v[226:229], v[130:133], v[46:49]
	v_exp_f32_e32 v102, v102
	v_mfma_f32_16x16x32_bf16 v[30:33], v[226:229], v[138:141], v[30:33]
	ds_read_b64_tr_b16 v[226:227], v205 offset:27680
	ds_read_b64_tr_b16 v[228:229], v205 offset:32288
	v_exp_f32_e32 v103, v103
	s_waitcnt lgkmcnt(10)
	v_mfma_f32_16x16x32_bf16 v[26:29], v[244:247], v[130:133], v[26:29]
	v_exp_f32_e32 v104, v104
	v_mfma_f32_16x16x32_bf16 v[22:25], v[244:247], v[138:141], v[22:25]
	ds_read_b64_tr_b16 v[244:245], v205 offset:27712
	ds_read_b64_tr_b16 v[246:247], v205 offset:32320
	v_exp_f32_e32 v105, v105
	s_waitcnt lgkmcnt(10)
	v_mfma_f32_16x16x32_bf16 v[18:21], v[248:251], v[130:133], v[18:21]
	v_exp_f32_e32 v118, v118
	v_mfma_f32_16x16x32_bf16 v[14:17], v[248:251], v[138:141], v[14:17]
	ds_read_b64_tr_b16 v[248:249], v205 offset:27744
	ds_read_b64_tr_b16 v[250:251], v205 offset:32352
	v_exp_f32_e32 v119, v119
	s_waitcnt lgkmcnt(10)
	v_mfma_f32_16x16x32_bf16 v[6:9], v[182:185], v[130:133], v[6:9]
	v_exp_f32_e32 v120, v120
	v_mfma_f32_16x16x32_bf16 v[10:13], v[182:185], v[138:141], v[10:13]
	ds_read_b64_tr_b16 v[182:183], v205 offset:27776
	ds_read_b64_tr_b16 v[184:185], v205 offset:32384
	v_exp_f32_e32 v121, v121
	s_waitcnt lgkmcnt(10)
	v_mfma_f32_16x16x32_bf16 v[66:69], v[186:189], v[130:133], v[66:69]
	v_exp_f32_e32 v106, v106
	v_mfma_f32_16x16x32_bf16 v[86:89], v[186:189], v[138:141], v[86:89]
	ds_read_b64_tr_b16 v[186:187], v205 offset:27808
	ds_read_b64_tr_b16 v[188:189], v205 offset:32416
	v_exp_f32_e32 v107, v107
	v_mfma_f32_16x16x32_bf16 v[94:97], v[74:77], v[134:137], v[94:97]
	v_exp_f32_e32 v108, v108
	v_mfma_f32_16x16x32_bf16 v[90:93], v[74:77], v[142:145], v[90:93]
	v_exp_f32_e32 v109, v109
	s_waitcnt lgkmcnt(10)
	v_mfma_f32_16x16x32_bf16 v[82:85], v[190:193], v[134:137], v[82:85]
	v_exp_f32_e32 v122, v122
	v_mfma_f32_16x16x32_bf16 v[78:81], v[190:193], v[142:145], v[78:81]
	ds_read_b64_tr_b16 v[190:191], v205 offset:27840
	ds_read_b64_tr_b16 v[192:193], v205 offset:32448
	v_exp_f32_e32 v123, v123
	s_waitcnt lgkmcnt(10)
	v_mfma_f32_16x16x32_bf16 v[70:73], v[226:229], v[134:137], v[70:73]
	v_exp_f32_e32 v124, v124
	v_mfma_f32_16x16x32_bf16 v[62:65], v[226:229], v[142:145], v[62:65]
	ds_read_b64_tr_b16 v[226:227], v205 offset:27872
	ds_read_b64_tr_b16 v[228:229], v205 offset:32480
	v_exp_f32_e32 v125, v125
	s_waitcnt lgkmcnt(10)
	v_mfma_f32_16x16x32_bf16 v[58:61], v[244:247], v[134:137], v[58:61]
	v_exp_f32_e32 v110, v110
	v_mfma_f32_16x16x32_bf16 v[54:57], v[244:247], v[142:145], v[54:57]
	v_exp_f32_e32 v111, v111
	s_waitcnt lgkmcnt(8)
	v_mfma_f32_16x16x32_bf16 v[46:49], v[248:251], v[134:137], v[46:49]
	v_exp_f32_e32 v112, v112
	v_mfma_f32_16x16x32_bf16 v[30:33], v[248:251], v[142:145], v[30:33]
	v_exp_f32_e32 v113, v113
	s_waitcnt lgkmcnt(6)
	v_mfma_f32_16x16x32_bf16 v[26:29], v[182:185], v[134:137], v[26:29]
	v_exp_f32_e32 v126, v126
	s_waitcnt vmcnt(3)
	ds_write_b128 v238, v[146:149]
	v_mfma_f32_16x16x32_bf16 v[22:25], v[182:185], v[142:145], v[22:25]
	v_exp_f32_e32 v127, v127
	s_waitcnt lgkmcnt(5)
	v_mfma_f32_16x16x32_bf16 v[18:21], v[186:189], v[134:137], v[18:21]
	v_exp_f32_e32 v128, v128
	s_waitcnt vmcnt(2)
	ds_write_b128 v238, v[150:153] offset:9216
	v_mfma_f32_16x16x32_bf16 v[14:17], v[186:189], v[142:145], v[14:17]
	v_exp_f32_e32 v129, v129
	s_waitcnt lgkmcnt(4)
	v_mfma_f32_16x16x32_bf16 v[6:9], v[190:193], v[134:137], v[6:9]
	v_cvt_pk_bf16_f32 v130, v98, v99
	v_cvt_pk_bf16_f32 v131, v100, v101
	s_waitcnt vmcnt(1)
	ds_write_b128 v239, v[154:157] offset:18432
	v_mfma_f32_16x16x32_bf16 v[10:13], v[190:193], v[142:145], v[10:13]
	v_cvt_pk_bf16_f32 v132, v102, v103
	v_cvt_pk_bf16_f32 v133, v104, v105
	s_waitcnt lgkmcnt(3)
	v_mfma_f32_16x16x32_bf16 v[66:69], v[226:229], v[134:137], v[66:69]
	v_cvt_pk_bf16_f32 v138, v114, v115
	v_cvt_pk_bf16_f32 v139, v116, v117
	s_waitcnt vmcnt(0)
	ds_write_b128 v239, v[158:161] offset:27648
	v_mfma_f32_16x16x32_bf16 v[86:89], v[226:229], v[142:145], v[86:89]
	v_cvt_pk_bf16_f32 v140, v118, v119
	v_cvt_pk_bf16_f32 v141, v120, v121
	s_waitcnt lgkmcnt(0)
	s_barrier
; #define LAS __attribute__((address_space(3)))
; __device__ __forceinline__ f32x4 mfma16(bf16x8 a, bf16x8 b, f32x4 c) { return __builtin_amdgcn_mfma_f32_16x16x32_bf16(a, b, c, 0, 0, 0); }
; #define BAR_LDS() do { asm volatile("s_waitcnt lgkmcnt(0)" ::: "memory"); __builtin_amdgcn_s_barrier(); asm volatile("" ::: "memory"); } while (0)
; __device__ __forceinline__ void attn_step_fast(const LAS char* Kb, const LAS char* Vb, int lane, const bf16x8 (&qf)[2][2], const f32x4 negM, const bf16x8 onesf, f32x4 (&O)[2][8], f32x4 (&Oe)[2]) {
;     ...
;     bf16x8 va[8], vb[8];
; #pragma unroll
;     for (int nb = 0; nb < 8; ++nb) va[nb] = trfrag(Vb, APIT, 0, 16 * nb, lane);
; #pragma unroll
;     for (int nb = 0; nb < 8; ++nb) vb[nb] = trfrag(Vb, APIT, 32, 16 * nb, lane);
;     __builtin_amdgcn_sched_barrier(0);
;     Oe[0] = mfma16(onesf, p0[0], Oe[0]);
; #pragma unroll
;     for (int nb = 0; nb < 8; ++nb) O[0][nb] = mfma16(va[nb], p0[0], O[0][nb]);
;     Oe[0] = mfma16(onesf, p0[1], Oe[0]);
; #pragma unroll
;     for (int nb = 0; nb < 8; ++nb) O[0][nb] = mfma16(vb[nb], p0[1], O[0][nb]);
;     ATT_EXPPACK(s1, p1);
; #pragma unroll
;     for (int i = 0; i < 18; ++i) { __builtin_amdgcn_sched_group_barrier(0x008, 1, 0); __builtin_amdgcn_sched_group_barrier(0x002, 2, 0); }
;     __builtin_amdgcn_sched_barrier(0);
;     Oe[1] = mfma16(onesf, p1[0], Oe[1]);
; #pragma unroll
;     for (int nb = 0; nb < 8; ++nb) O[1][nb] = mfma16(va[nb], p1[0], O[1][nb]);
;     Oe[1] = mfma16(onesf, p1[1], Oe[1]);
; #pragma unroll
;     for (int nb = 0; nb < 8; ++nb) O[1][nb] = mfma16(vb[nb], p1[1], O[1][nb]);
; __device__ __forceinline__ void attn_item(LAS char* lds, bf16_t* proj, int bl, int h, int qb, float lam, float oscale, const float* gdh, float smax) {
;     ...
;     for (; t < NT - 2; ++t) {
;         ATT_LOAD(t + 1);
;         const LAS char* Kb = lds + (t & 1) * ABUF;
;     ...
;         attn_step_fast(Kb, Kb + ATILE, lane, qf, negM, onesf, O, Oe);
;     ...
;         { bf16x8 pq[2][2]; attn_qkexp(Kb, 64 * t, q0, wid, lane, g, qpos, qf, negM, pq); attn_pv(Kb + ATILE, lane, pq, onesf, O, Oe); }
;     ...
;         ATT_STORE((t + 1) & 1);
;         BAR_LDS();
;     }
;     bf16x8 pf[2][2];
;     for (; t < NT; ++t) {
;         const int k0 = 64 * t;
;         if (t + 1 < NT) ATT_LOAD(t + 1);
	s_xor_b32 s49, s49, 0x9000
	s_xor_b32 s50, s50, 0x9000
	s_add_i32 s47, s47, -1
	s_cmp_lg_u32 s47, 0
	s_cbranch_scc1 .Lmy_attn_loop
	v_add_u32_e32 v181, s49, v230
	v_add_u32_e32 v205, s50, v231
	v_lshl_add_u64 v[240:241], v[172:173], 0, s[8:9]
	global_load_dwordx4 v[154:157], v[240:241], off
	v_lshl_add_u64 v[240:241], v[172:173], 0, s[10:11]
	global_load_dwordx4 v[158:161], v[240:241], off
	v_cvt_pk_bf16_f32 v134, v106, v107
	v_cvt_pk_bf16_f32 v135, v108, v109
	v_cvt_pk_bf16_f32 v136, v110, v111
	v_cvt_pk_bf16_f32 v137, v112, v113
	v_cvt_pk_bf16_f32 v142, v122, v123
	v_cvt_pk_bf16_f32 v143, v124, v125
	v_cvt_pk_bf16_f32 v144, v126, v127
	v_cvt_pk_bf16_f32 v145, v128, v129
	ds_read_b64_tr_b16 v[182:183], v205 offset:18432
	ds_read_b64_tr_b16 v[184:185], v205 offset:23040
	ds_read_b64_tr_b16 v[186:187], v205 offset:18464
	ds_read_b64_tr_b16 v[188:189], v205 offset:23072
	ds_read_b64_tr_b16 v[190:191], v205 offset:18496
	ds_read_b64_tr_b16 v[192:193], v205 offset:23104
	ds_read_b64_tr_b16 v[226:227], v205 offset:18528
	ds_read_b64_tr_b16 v[228:229], v205 offset:23136
	ds_read_b64_tr_b16 v[244:245], v205 offset:18560
	ds_read_b64_tr_b16 v[246:247], v205 offset:23168
	ds_read_b64_tr_b16 v[248:249], v205 offset:18592
	ds_read_b64_tr_b16 v[250:251], v205 offset:23200
	v_add_u32_e32 v238, s50, v179
	v_add_u32_e32 v239, s49, v179
	v_mfma_f32_16x16x32_bf16 v[94:97], v[74:77], v[130:133], v[94:97]
	v_mfma_f32_16x16x32_bf16 v[90:93], v[74:77], v[138:141], v[90:93]
	s_waitcnt lgkmcnt(10)
	v_mfma_f32_16x16x32_bf16 v[82:85], v[182:185], v[130:133], v[82:85]
	v_mfma_f32_16x16x32_bf16 v[78:81], v[182:185], v[138:141], v[78:81]
	ds_read_b64_tr_b16 v[182:183], v205 offset:18624
	ds_read_b64_tr_b16 v[184:185], v205 offset:23232
	s_waitcnt lgkmcnt(10)
	v_mfma_f32_16x16x32_bf16 v[70:73], v[186:189], v[130:133], v[70:73]
	v_mfma_f32_16x16x32_bf16 v[62:65], v[186:189], v[138:141], v[62:65]
	ds_read_b64_tr_b16 v[186:187], v205 offset:18656
	ds_read_b64_tr_b16 v[188:189], v205 offset:23264
	s_waitcnt lgkmcnt(10)
	v_mfma_f32_16x16x32_bf16 v[58:61], v[190:193], v[130:133], v[58:61]
	v_mfma_f32_16x16x32_bf16 v[54:57], v[190:193], v[138:141], v[54:57]
	ds_read_b64_tr_b16 v[190:191], v205 offset:27648
	ds_read_b64_tr_b16 v[192:193], v205 offset:32256
	s_waitcnt lgkmcnt(10)
	v_mfma_f32_16x16x32_bf16 v[46:49], v[226:229], v[130:133], v[46:49]
	v_mfma_f32_16x16x32_bf16 v[30:33], v[226:229], v[138:141], v[30:33]
	ds_read_b64_tr_b16 v[226:227], v205 offset:27680
	ds_read_b64_tr_b16 v[228:229], v205 offset:32288
	s_waitcnt lgkmcnt(10)
	v_mfma_f32_16x16x32_bf16 v[26:29], v[244:247], v[130:133], v[26:29]
	v_mfma_f32_16x16x32_bf16 v[22:25], v[244:247], v[138:141], v[22:25]
	ds_read_b64_tr_b16 v[244:245], v205 offset:27712
	ds_read_b64_tr_b16 v[246:247], v205 offset:32320
	s_waitcnt lgkmcnt(10)
	v_mfma_f32_16x16x32_bf16 v[18:21], v[248:251], v[130:133], v[18:21]
	v_mfma_f32_16x16x32_bf16 v[14:17], v[248:251], v[138:141], v[14:17]
	ds_read_b64_tr_b16 v[248:249], v205 offset:27744
	ds_read_b64_tr_b16 v[250:251], v205 offset:32352
	s_waitcnt lgkmcnt(10)
	v_mfma_f32_16x16x32_bf16 v[6:9], v[182:185], v[130:133], v[6:9]
	v_mfma_f32_16x16x32_bf16 v[10:13], v[182:185], v[138:141], v[10:13]
	ds_read_b64_tr_b16 v[182:183], v205 offset:27776
	ds_read_b64_tr_b16 v[184:185], v205 offset:32384
	s_waitcnt lgkmcnt(10)
	v_mfma_f32_16x16x32_bf16 v[66:69], v[186:189], v[130:133], v[66:69]
	v_mfma_f32_16x16x32_bf16 v[86:89], v[186:189], v[138:141], v[86:89]
	ds_read_b64_tr_b16 v[186:187], v205 offset:27808
	ds_read_b64_tr_b16 v[188:189], v205 offset:32416
	v_mfma_f32_16x16x32_bf16 v[94:97], v[74:77], v[134:137], v[94:97]
	v_mfma_f32_16x16x32_bf16 v[90:93], v[74:77], v[142:145], v[90:93]
	s_waitcnt lgkmcnt(10)
	v_mfma_f32_16x16x32_bf16 v[82:85], v[190:193], v[134:137], v[82:85]
	v_mfma_f32_16x16x32_bf16 v[78:81], v[190:193], v[142:145], v[78:81]
	ds_read_b64_tr_b16 v[190:191], v205 offset:27840
	ds_read_b64_tr_b16 v[192:193], v205 offset:32448
	s_waitcnt lgkmcnt(10)
	v_mfma_f32_16x16x32_bf16 v[70:73], v[226:229], v[134:137], v[70:73]
	v_mfma_f32_16x16x32_bf16 v[62:65], v[226:229], v[142:145], v[62:65]
	ds_read_b64_tr_b16 v[226:227], v205 offset:27872
	ds_read_b64_tr_b16 v[228:229], v205 offset:32480
	s_waitcnt lgkmcnt(10)
	v_mfma_f32_16x16x32_bf16 v[58:61], v[244:247], v[134:137], v[58:61]
	v_mfma_f32_16x16x32_bf16 v[54:57], v[244:247], v[142:145], v[54:57]
	s_waitcnt lgkmcnt(8)
	v_mfma_f32_16x16x32_bf16 v[46:49], v[248:251], v[134:137], v[46:49]
	v_mfma_f32_16x16x32_bf16 v[30:33], v[248:251], v[142:145], v[30:33]
	s_waitcnt lgkmcnt(6)
	v_mfma_f32_16x16x32_bf16 v[26:29], v[182:185], v[134:137], v[26:29]
	s_waitcnt vmcnt(1)
	ds_write_b128 v239, v[154:157] offset:18432
	v_mfma_f32_16x16x32_bf16 v[22:25], v[182:185], v[142:145], v[22:25]
	s_waitcnt lgkmcnt(5)
	v_mfma_f32_16x16x32_bf16 v[18:21], v[186:189], v[134:137], v[18:21]
	s_waitcnt vmcnt(0)
	ds_write_b128 v239, v[158:161] offset:27648
	v_mfma_f32_16x16x32_bf16 v[14:17], v[186:189], v[142:145], v[14:17]
	s_waitcnt lgkmcnt(4)
	v_mfma_f32_16x16x32_bf16 v[6:9], v[190:193], v[134:137], v[6:9]
	v_mfma_f32_16x16x32_bf16 v[10:13], v[190:193], v[142:145], v[10:13]
	s_waitcnt lgkmcnt(2)
	v_mfma_f32_16x16x32_bf16 v[66:69], v[226:229], v[134:137], v[66:69]
	v_mfma_f32_16x16x32_bf16 v[86:89], v[226:229], v[142:145], v[86:89]
	s_waitcnt lgkmcnt(0)
	s_barrier
